# mlp2 context-row 64x64 tiles: hand-written k-loop with an 8-slot LDS ring (seven K-slices of LDS-DMA in flight instead of two)
# baseline (speedup 1.0000x reference)
; template <int MI, int NI>
; DI void gemm256(f32x4 (&acc)[MI][NI], const u16* __restrict__ A, int lda, const u16* __restrict__ Bt, int ldb, int K, int m0, int n0, char* smem) {
;     ...
;   const int nk = K >> 5;
;   G256_ISSUE(0, 0);
;   if (nk > 1) G256_ISSUE(1, 32);
;   const int foff = lr * 64 + ((lq ^ ((lr >> 3) << 1)) * 16);
;   int st = 0;
;   for (int kt = 0; kt < nk; ++kt) {
;     if (kt + 1 < nk) asm volatile("s_waitcnt vmcnt(%0) lgkmcnt(0)" :: "n"(LPS) : "memory");
;     else asm volatile("s_waitcnt vmcnt(0) lgkmcnt(0)" ::: "memory");
;     __builtin_amdgcn_s_barrier();
;     __builtin_amdgcn_s_setprio(1);
;     const char* sb = smem + st * STAGE + foff;
;     bf16x8 af[MI], bfr[NI];
; #pragma unroll
;     for (int mi = 0; mi < MI; ++mi) af[mi] = *(const bf16x8*)(sb + (wr * MI + mi) * 1024);
; #pragma unroll
;     for (int ni = 0; ni < NI; ++ni) bfr[ni] = *(const bf16x8*)(sb + ABYTES + (wc * NI + ni) * 1024);
;     __builtin_amdgcn_sched_barrier(0x0);
;     if (kt + 2 < nk) { const int s2 = st >= 1 ? st - 1 : 2; G256_ISSUE(s2, (kt + 2) * 32); }
;     __builtin_amdgcn_s_setprio(0);
; #pragma unroll
;     for (int mi = 0; mi < MI; ++mi)
; #pragma unroll
;       for (int ni = 0; ni < NI; ++ni)
;         acc[mi][ni] = __builtin_amdgcn_mfma_f32_16x16x32_bf16(bfr[ni], af[mi], acc[mi][ni], 0, 0, 0);
;     st = st == 2 ? 0 : st + 1;
;   }
; template <int MI, int NI>
; DI void resid_tile(const u16* A, int K, const u16* Bt, const float* gate, const float* xl_in, const float* xc_in, float* xl_out, float* xc_out,
;                    int m0, int n0, char* smem) {
;     ...
; #pragma unroll
;   for (int mi = 0; mi < MI; ++mi) {
;     const int m = m0 + wr * 16 * MI + mi * 16 + lr;
;     const int b9 = m < NTL ? m >> 12 : 8;
;     const float* xi = xrow(xl_in, xc_in, m);
;     float* xo = m < NTL ? xl_out + (size_t)m * D : xc_out + (size_t)(m - NTL) * D;
; #pragma unroll
;     for (int ni = 0; ni < NI; ++ni) {
;       const int n = n0 + wc * 16 * NI + ni * 16 + lq * 4;
;       const float4 g = *(const float4*)(gate + (size_t)b9 * 6144 + n);
;       const float4 xv = *(const float4*)(xi + n);
;       float4 ov;
;       ov.x = xv.x + g.x * acc[mi][ni][0]; ov.y = xv.y + g.y * acc[mi][ni][1]; ov.z = xv.z + g.z * acc[mi][ni][2]; ov.w = xv.w + g.w * acc[mi][ni][3];
;       *(float4*)(xo + n) = ov;
;     }
.LBB0_967:
	s_mov_b64 s[98:99], 0x47e1000
	v_lshl_add_u64 v[44:45], v[18:19], 0, s[98:99]
	s_mov_b64 s[98:99], 0x2061000
	v_lshl_add_u64 v[46:47], v[20:21], 0, s[98:99]
	v_readfirstlane_b32 s11, v27
	s_mov_b64 s[98:99], 0x100
	v_lshl_add_u64 v[48:49], v[44:45], 0, s[98:99]
	v_lshl_add_u64 v[50:51], v[46:47], 0, s[98:99]
	s_add_i32 m0, s11, 0x4000
	s_nop 0
	global_load_lds_dwordx4 v[48:49], off
	s_add_i32 m0, s11, 0x5000
	s_nop 0
	global_load_lds_dwordx4 v[50:51], off
	s_mov_b64 s[98:99], 0x180
	v_lshl_add_u64 v[48:49], v[44:45], 0, s[98:99]
	v_lshl_add_u64 v[50:51], v[46:47], 0, s[98:99]
	s_add_i32 m0, s11, 0x6000
	s_nop 0
	global_load_lds_dwordx4 v[48:49], off
	s_add_i32 m0, s11, 0x7000
	s_nop 0
	global_load_lds_dwordx4 v[50:51], off
	s_mov_b64 s[98:99], 0x200
	v_lshl_add_u64 v[48:49], v[44:45], 0, s[98:99]
	v_lshl_add_u64 v[50:51], v[46:47], 0, s[98:99]
	s_add_i32 m0, s11, 0x8000
	s_nop 0
	global_load_lds_dwordx4 v[48:49], off
	s_add_i32 m0, s11, 0x9000
	s_nop 0
	global_load_lds_dwordx4 v[50:51], off
	s_mov_b64 s[98:99], 0x280
	v_lshl_add_u64 v[48:49], v[44:45], 0, s[98:99]
	v_lshl_add_u64 v[50:51], v[46:47], 0, s[98:99]
	s_add_i32 m0, s11, 0xa000
	s_nop 0
	global_load_lds_dwordx4 v[48:49], off
	s_add_i32 m0, s11, 0xb000
	s_nop 0
	global_load_lds_dwordx4 v[50:51], off
	s_mov_b64 s[98:99], 0x300
	v_lshl_add_u64 v[48:49], v[44:45], 0, s[98:99]
	v_lshl_add_u64 v[50:51], v[46:47], 0, s[98:99]
	s_add_i32 m0, s11, 0xc000
	s_nop 0
	global_load_lds_dwordx4 v[48:49], off
	s_add_i32 m0, s11, 0xd000
	s_nop 0
	global_load_lds_dwordx4 v[50:51], off
	s_mov_b32 s9, 0
	s_mov_b32 s0, 0
	s_mov_b32 s99, 0
.Lc22m_loop:
	s_waitcnt vmcnt(12) lgkmcnt(0)
	s_barrier
	s_lshl_b32 s10, s9, 13
	v_or_b32_e32 v0, s10, v24
	v_add_u32_e32 v28, v0, v26
	v_add_u32_e32 v32, v0, v25
	v_add_u32_e32 v0, v0, v23
	ds_read_b128 v[28:31], v28
	ds_read_b128 v[32:35], v32
	ds_read_b128 v[36:39], v0 offset:4096
	ds_read_b128 v[40:43], v0 offset:5120
	s_add_i32 s10, s0, 7
	s_min_u32 s10, s10, 0x7f
	s_lshl_b32 s98, s10, 7
	v_lshl_add_u64 v[48:49], v[44:45], 0, s[98:99]
	v_lshl_add_u64 v[50:51], v[46:47], 0, s[98:99]
	s_add_i32 s10, s9, 7
	s_and_b32 s10, s10, 7
	s_lshl_b32 s10, s10, 13
	s_add_i32 s10, s10, s11
	s_mov_b32 m0, s10
	s_nop 0
	global_load_lds_dwordx4 v[48:49], off
	s_add_i32 m0, s10, 0x1000
	s_nop 0
	global_load_lds_dwordx4 v[50:51], off
	s_waitcnt lgkmcnt(0)
	v_mfma_f32_16x16x32_bf16 v[14:17], v[36:39], v[28:31], v[14:17]
	v_mfma_f32_16x16x32_bf16 v[10:13], v[40:43], v[28:31], v[10:13]
	v_mfma_f32_16x16x32_bf16 v[6:9], v[36:39], v[32:35], v[6:9]
	v_mfma_f32_16x16x32_bf16 v[2:5], v[40:43], v[32:35], v[2:5]
	s_add_i32 s9, s9, 1
	s_and_b32 s9, s9, 7
	s_add_i32 s0, s0, 1
	s_cmpk_lg_i32 s0, 0x80
	s_cbranch_scc1 .Lc22m_loop
	s_waitcnt vmcnt(0)
	s_barrier
	v_bfe_u32 v0, v22, 6, 1
	v_ashrrev_i32_e32 v40, 7, v22
	v_and_b32_e32 v41, 15, v22
	v_bfe_u32 v22, v22, 4, 2
	v_lshlrev_b32_e32 v0, 5, v0
	v_mov_b32_e32 v36, s95
	v_mov_b32_e32 v37, s49
	v_mov_b32_e32 v38, s94
	v_mov_b32_e32 v39, s48
	s_nop 0
	v_lshlrev_b32_e32 v18, 5, v40
	v_add3_u32 v26, v41, s8, v18
	v_lshlrev_b32_e32 v18, 2, v22
	v_add3_u32 v18, v18, s7, v0
	v_min_i32_e32 v0, 0x8000, v26
	v_cmp_gt_i32_e32 vcc, s58, v26
	v_ashrrev_i32_e32 v28, 12, v0
	v_add_u32_e32 v0, 0xffff8000, v26
	v_ashrrev_i32_e32 v27, 31, v26
	v_cndmask_b32_e32 v21, 0, v27, vcc
	v_cndmask_b32_e32 v20, v0, v26, vcc
	v_cndmask_b32_e32 v23, v36, v37, vcc
	v_cndmask_b32_e32 v22, v38, v39, vcc
	v_lshlrev_b64 v[20:21], 12, v[20:21]
	v_lshl_add_u64 v[20:21], v[22:23], 0, v[20:21]
	v_lshlrev_b64 v[22:23], 12, v[26:27]
	v_lshlrev_b64 v[24:25], 12, v[0:1]
	v_lshl_add_u64 v[22:23], s[48:49], 0, v[22:23]
	v_lshl_add_u64 v[24:25], s[94:95], 0, v[24:25]
	v_ashrrev_i32_e32 v19, 31, v18
	v_cndmask_b32_e32 v23, v25, v23, vcc
	v_cndmask_b32_e32 v22, v24, v22, vcc
	v_mul_hi_i32_i24_e32 v25, 0x6000, v28
	v_mul_i32_i24_e32 v24, 0x6000, v28
	v_lshl_add_u64 v[24:25], s[82:83], 0, v[24:25]
	v_lshlrev_b64 v[28:29], 2, v[18:19]
	v_lshl_add_u64 v[30:31], v[24:25], 0, v[28:29]
	v_lshl_add_u64 v[32:33], v[20:21], 0, v[28:29]
	v_lshl_add_u64 v[34:35], v[22:23], 0, v[28:29]
	flat_load_dwordx4 v[18:21], v[30:31]
	flat_load_dwordx4 v[22:25], v[32:33]
	s_waitcnt vmcnt(0) lgkmcnt(0)
	v_pk_fma_f32 v[14:15], v[14:15], v[18:19], v[22:23]
	v_pk_fma_f32 v[16:17], v[16:17], v[20:21], v[24:25]
	flat_store_dwordx4 v[34:35], v[14:17]
	flat_load_dwordx4 v[14:17], v[30:31] offset:64
	s_nop 0
	flat_load_dwordx4 v[18:21], v[32:33] offset:64
	s_waitcnt vmcnt(0) lgkmcnt(0)
	v_pk_fma_f32 v[10:11], v[10:11], v[14:15], v[18:19]
	v_pk_fma_f32 v[12:13], v[12:13], v[16:17], v[20:21]
	flat_store_dwordx4 v[34:35], v[10:13] offset:64
	s_nop 1
	v_add_u32_e32 v10, 16, v26
	v_min_i32_e32 v0, 0x8000, v10
	v_cmp_gt_i32_e32 vcc, s58, v10
	v_ashrrev_i32_e32 v16, 12, v0
	v_add_u32_e32 v0, 0xffff8010, v26
	v_ashrrev_i32_e32 v11, 31, v10
	v_cndmask_b32_e32 v13, 0, v11, vcc
	v_cndmask_b32_e32 v12, v0, v10, vcc
	v_cndmask_b32_e32 v15, v36, v37, vcc
	v_cndmask_b32_e32 v14, v38, v39, vcc
	v_lshlrev_b64 v[12:13], 12, v[12:13]
	v_lshl_add_u64 v[12:13], v[14:15], 0, v[12:13]
	v_lshlrev_b64 v[10:11], 12, v[10:11]
	v_lshlrev_b64 v[14:15], 12, v[0:1]
	v_lshl_add_u64 v[10:11], s[48:49], 0, v[10:11]
	v_lshl_add_u64 v[14:15], s[94:95], 0, v[14:15]
	v_cndmask_b32_e32 v11, v15, v11, vcc
	v_cndmask_b32_e32 v10, v14, v10, vcc
	v_mul_hi_i32_i24_e32 v15, 0x6000, v16
	v_mul_i32_i24_e32 v14, 0x6000, v16
	v_lshl_add_u64 v[14:15], s[82:83], 0, v[14:15]
	v_lshl_add_u64 v[18:19], v[14:15], 0, v[28:29]
	v_lshl_add_u64 v[20:21], v[12:13], 0, v[28:29]
	v_lshl_add_u64 v[22:23], v[10:11], 0, v[28:29]
	flat_load_dwordx4 v[10:13], v[18:19]
	flat_load_dwordx4 v[14:17], v[20:21]
	s_waitcnt vmcnt(0) lgkmcnt(0)
	v_pk_fma_f32 v[6:7], v[6:7], v[10:11], v[14:15]
	v_pk_fma_f32 v[8:9], v[8:9], v[12:13], v[16:17]
	flat_store_dwordx4 v[22:23], v[6:9]
	flat_load_dwordx4 v[6:9], v[18:19] offset:64
	s_nop 0
	flat_load_dwordx4 v[10:13], v[20:21] offset:64
	s_waitcnt vmcnt(0) lgkmcnt(0)
	v_pk_fma_f32 v[2:3], v[2:3], v[6:7], v[10:11]
	v_pk_fma_f32 v[4:5], v[4:5], v[8:9], v[12:13]
	flat_store_dwordx4 v[22:23], v[2:5] offset:64
	s_add_i32 s4, s4, s79
	s_add_i32 s5, s5, s40
	s_add_i32 s6, s6, s41
	s_cmpk_gt_i32 s4, 0x1ff
	s_cbranch_scc0 .LBB0_966
